# speedup vs baseline: 1.0163x; 1.0024x over previous
; __device__ __forceinline__ void dsa_tile(const Params& p, unsigned char* smem, int tile) {
;     ...
;         u32x4 yf[16][2];
; #pragma unroll
;         for (int h = 0; h < 16; ++h)
; #pragma unroll
;             for (int ks = 0; ks < 2; ++ks) yf[h][ks] = *(const u32x4*)(iqs + fr * 2048 + (((h * 8 + ks * 4 + fq) ^ fr) * 16));
;         u32x4 chi[2], clo[2];
; #pragma unroll
;         for (int ks = 0; ks < 2; ++ks) {
;             float c[8];
; #pragma unroll
;             for (int e = 0; e < 8; ++e) c[e] = 0.f;
; #pragma unroll
;             for (int h = 0; h < 16; ++h) { const float wh = wl[h * 16 + fr]; float f[8]; unpack8(yf[h][ks], f);
; #pragma unroll
;                 for (int e = 0; e < 8; ++e) c[e] += wh * f[e]; }
.LBB0_287:
	s_or_b64 exec, exec, s[12:13]
	v_bfe_u32 v120, v152, 4, 2
	s_movk_i32 s4, 0x44
	v_bitop3_b32 v65, v120, v153, s4 bitop3:0x36
	s_movk_i32 s4, 0x48
	v_bitop3_b32 v72, v120, v153, s4 bitop3:0x36
	s_movk_i32 s4, 0x4c
	v_bitop3_b32 v73, v120, v153, s4 bitop3:0x36
	s_movk_i32 s4, 0x50
	v_bitop3_b32 v80, v120, v153, s4 bitop3:0x36
	s_movk_i32 s4, 0x54
	v_bitop3_b32 v81, v120, v153, s4 bitop3:0x36
	s_movk_i32 s4, 0x58
	v_bitop3_b32 v88, v120, v153, s4 bitop3:0x36
	s_movk_i32 s4, 0x5c
	v_bitop3_b32 v89, v120, v153, s4 bitop3:0x36
	s_movk_i32 s4, 0x60
	v_bitop3_b32 v96, v120, v153, s4 bitop3:0x36
	s_movk_i32 s4, 0x64
	v_bitop3_b32 v97, v120, v153, s4 bitop3:0x36
	s_movk_i32 s4, 0x68
	v_bitop3_b32 v104, v120, v153, s4 bitop3:0x36
	s_movk_i32 s4, 0x6c
	v_bitop3_b32 v105, v120, v153, s4 bitop3:0x36
	s_movk_i32 s4, 0x70
	v_bitop3_b32 v112, v120, v153, s4 bitop3:0x36
	s_movk_i32 s4, 0x74
	v_bitop3_b32 v113, v120, v153, s4 bitop3:0x36
	s_movk_i32 s4, 0x78
	v_bitop3_b32 v122, v120, v153, s4 bitop3:0x36
	s_movk_i32 s4, 0x7c
	v_lshl_add_u32 v121, v153, 11, 0
	v_xor_b32_e32 v0, v120, v153
	v_bitop3_b32 v1, v120, v153, 4 bitop3:0x36
	v_bitop3_b32 v8, v120, v153, 8 bitop3:0x36
	v_bitop3_b32 v9, v120, v153, 12 bitop3:0x36
	v_bitop3_b32 v16, v120, v153, 16 bitop3:0x36
	v_bitop3_b32 v17, v120, v153, 20 bitop3:0x36
	v_bitop3_b32 v24, v120, v153, 24 bitop3:0x36
	v_bitop3_b32 v25, v120, v153, 28 bitop3:0x36
	v_bitop3_b32 v32, v120, v153, 32 bitop3:0x36
	v_bitop3_b32 v33, v120, v153, 36 bitop3:0x36
	v_bitop3_b32 v40, v120, v153, 40 bitop3:0x36
	v_bitop3_b32 v41, v120, v153, 44 bitop3:0x36
	v_bitop3_b32 v48, v120, v153, 48 bitop3:0x36
	v_bitop3_b32 v49, v120, v153, 52 bitop3:0x36
	v_bitop3_b32 v56, v120, v153, 56 bitop3:0x36
	v_bitop3_b32 v57, v120, v153, 60 bitop3:0x36
	v_bitop3_b32 v64, v120, v153, 64 bitop3:0x36
	v_bitop3_b32 v120, v120, v153, s4 bitop3:0x36
	v_lshl_add_u32 v154, v153, 2, 0
	v_lshl_add_u32 v0, v0, 4, v121
	v_lshl_add_u32 v4, v1, 4, v121
	v_lshl_add_u32 v8, v8, 4, v121
	v_lshl_add_u32 v12, v9, 4, v121
	v_lshl_add_u32 v16, v16, 4, v121
	v_lshl_add_u32 v20, v17, 4, v121
	v_lshl_add_u32 v24, v24, 4, v121
	v_lshl_add_u32 v28, v25, 4, v121
	v_lshl_add_u32 v32, v32, 4, v121
	v_lshl_add_u32 v36, v33, 4, v121
	v_lshl_add_u32 v40, v40, 4, v121
	v_lshl_add_u32 v44, v41, 4, v121
	v_lshl_add_u32 v48, v48, 4, v121
	v_lshl_add_u32 v52, v49, 4, v121
	v_lshl_add_u32 v56, v56, 4, v121
	v_lshl_add_u32 v60, v57, 4, v121
	v_lshl_add_u32 v64, v64, 4, v121
	v_lshl_add_u32 v68, v65, 4, v121
	v_lshl_add_u32 v72, v72, 4, v121
	v_lshl_add_u32 v76, v73, 4, v121
	v_lshl_add_u32 v80, v80, 4, v121
	v_lshl_add_u32 v84, v81, 4, v121
	v_lshl_add_u32 v88, v88, 4, v121
	v_lshl_add_u32 v92, v89, 4, v121
	v_lshl_add_u32 v96, v96, 4, v121
	v_lshl_add_u32 v100, v97, 4, v121
	v_lshl_add_u32 v104, v104, 4, v121
	v_lshl_add_u32 v108, v105, 4, v121
	v_lshl_add_u32 v112, v112, 4, v121
	v_lshl_add_u32 v116, v113, 4, v121
	v_lshl_add_u32 v122, v122, 4, v121
	v_lshl_add_u32 v124, v120, 4, v121
	v_add_u32_e32 v155, 0xa000, v154
	s_waitcnt lgkmcnt(0)
	s_barrier
	ds_read_b128 v[0:3], v0 offset:8192
	ds_read_b128 v[4:7], v4 offset:8192
	ds_read_b128 v[8:11], v8 offset:8192
	ds_read_b128 v[12:15], v12 offset:8192
	ds_read_b128 v[16:19], v16 offset:8192
	ds_read_b128 v[20:23], v20 offset:8192
	ds_read_b128 v[24:27], v24 offset:8192
	ds_read_b128 v[28:31], v28 offset:8192
	ds_read_b128 v[32:35], v32 offset:8192
	ds_read_b128 v[36:39], v36 offset:8192
	ds_read_b128 v[40:43], v40 offset:8192
	ds_read_b128 v[44:47], v44 offset:8192
	ds_read_b128 v[48:51], v48 offset:8192
	ds_read_b128 v[52:55], v52 offset:8192
	ds_read_b128 v[56:59], v56 offset:8192
	ds_read_b128 v[60:63], v60 offset:8192
	ds_read_b128 v[64:67], v64 offset:8192
	ds_read_b128 v[68:71], v68 offset:8192
	ds_read_b128 v[72:75], v72 offset:8192
	ds_read_b128 v[76:79], v76 offset:8192
	ds_read_b128 v[80:83], v80 offset:8192
	ds_read_b128 v[84:87], v84 offset:8192
	ds_read_b128 v[88:91], v88 offset:8192
	ds_read_b128 v[92:95], v92 offset:8192
	ds_read_b128 v[96:99], v96 offset:8192
	ds_read_b128 v[100:103], v100 offset:8192
	ds_read_b128 v[104:107], v104 offset:8192
	ds_read_b128 v[108:111], v108 offset:8192
	ds_read_b128 v[112:115], v112 offset:8192
	ds_read_b128 v[116:119], v116 offset:8192
	ds_read_b128 v[120:123], v122 offset:8192
	ds_read_b128 v[124:127], v124 offset:8192
	ds_read2_b32 v[128:129], v155 offset1:16
	s_waitcnt lgkmcnt(14)
	v_lshlrev_b32_e32 v130, 16, v0
	v_and_b32_e32 v131, 0xffff0000, v0
	v_lshlrev_b32_e32 v132, 16, v1
	v_and_b32_e32 v133, 0xffff0000, v1
	v_lshlrev_b32_e32 v134, 16, v2
	v_and_b32_e32 v135, 0xffff0000, v2
	v_lshlrev_b32_e32 v136, 16, v3
	v_and_b32_e32 v137, 0xffff0000, v3
	s_waitcnt lgkmcnt(0)
	v_fma_f32 v138, v128, v130, 0
	v_fma_f32 v139, v128, v131, 0
	v_fma_f32 v132, v128, v132, 0
	v_fma_f32 v133, v128, v133, 0
	v_fma_f32 v134, v128, v134, 0
	v_fma_f32 v135, v128, v135, 0
	v_fma_f32 v136, v128, v136, 0
	v_fma_f32 v137, v128, v137, 0
	v_lshlrev_b32_e32 v128, 16, v8
	v_and_b32_e32 v130, 0xffff0000, v8
	v_lshlrev_b32_e32 v131, 16, v9
	v_and_b32_e32 v140, 0xffff0000, v9
	v_lshlrev_b32_e32 v141, 16, v10
	v_and_b32_e32 v142, 0xffff0000, v10
	v_lshlrev_b32_e32 v143, 16, v11
	v_and_b32_e32 v144, 0xffff0000, v11
	v_fmac_f32_e32 v138, v129, v128
	v_fmac_f32_e32 v139, v129, v130
	v_fmac_f32_e32 v132, v129, v131
	v_fmac_f32_e32 v133, v129, v140
	v_fmac_f32_e32 v134, v129, v141
	v_fmac_f32_e32 v135, v129, v142
	v_fmac_f32_e32 v136, v129, v143
	v_fmac_f32_e32 v137, v129, v144
	ds_read2_b32 v[128:129], v155 offset0:32 offset1:48
	v_lshlrev_b32_e32 v130, 16, v16
	v_and_b32_e32 v131, 0xffff0000, v16
	v_lshlrev_b32_e32 v140, 16, v17
	v_and_b32_e32 v141, 0xffff0000, v17
	v_lshlrev_b32_e32 v142, 16, v18
	v_and_b32_e32 v143, 0xffff0000, v18
	v_lshlrev_b32_e32 v144, 16, v19
	v_and_b32_e32 v145, 0xffff0000, v19
	s_waitcnt lgkmcnt(0)
; __device__ __forceinline__ void dsa_tile(const Params& p, unsigned char* smem, int tile) {
;     ...
;             for (int h = 0; h < 16; ++h) { const float wh = wl[h * 16 + fr]; float f[8]; unpack8(yf[h][ks], f);
; #pragma unroll
;                 for (int e = 0; e < 8; ++e) c[e] += wh * f[e]; }
	v_fmac_f32_e32 v138, v128, v130
	v_fmac_f32_e32 v139, v128, v131
	v_fmac_f32_e32 v132, v128, v140
	v_fmac_f32_e32 v133, v128, v141
	v_fmac_f32_e32 v134, v128, v142
	v_fmac_f32_e32 v135, v128, v143
	v_fmac_f32_e32 v136, v128, v144
	v_fmac_f32_e32 v137, v128, v145
	v_lshlrev_b32_e32 v128, 16, v24
	v_and_b32_e32 v130, 0xffff0000, v24
	v_lshlrev_b32_e32 v131, 16, v25
	v_and_b32_e32 v140, 0xffff0000, v25
	v_lshlrev_b32_e32 v141, 16, v26
	v_and_b32_e32 v142, 0xffff0000, v26
	v_lshlrev_b32_e32 v143, 16, v27
	v_and_b32_e32 v144, 0xffff0000, v27
	v_fmac_f32_e32 v138, v129, v128
	v_fmac_f32_e32 v139, v129, v130
	v_fmac_f32_e32 v132, v129, v131
	v_fmac_f32_e32 v133, v129, v140
	v_fmac_f32_e32 v134, v129, v141
	v_fmac_f32_e32 v135, v129, v142
	v_fmac_f32_e32 v136, v129, v143
	v_fmac_f32_e32 v137, v129, v144
	ds_read2_b32 v[128:129], v155 offset0:64 offset1:80
	v_lshlrev_b32_e32 v130, 16, v32
	v_and_b32_e32 v131, 0xffff0000, v32
	v_lshlrev_b32_e32 v140, 16, v33
	v_and_b32_e32 v141, 0xffff0000, v33
	v_lshlrev_b32_e32 v142, 16, v34
	v_and_b32_e32 v143, 0xffff0000, v34
	v_lshlrev_b32_e32 v144, 16, v35
	v_and_b32_e32 v145, 0xffff0000, v35
	s_waitcnt lgkmcnt(0)
	v_fmac_f32_e32 v138, v128, v130
	v_fmac_f32_e32 v139, v128, v131
	v_fmac_f32_e32 v132, v128, v140
	v_fmac_f32_e32 v133, v128, v141
	v_fmac_f32_e32 v134, v128, v142
	v_fmac_f32_e32 v135, v128, v143
	v_fmac_f32_e32 v136, v128, v144
	v_fmac_f32_e32 v137, v128, v145
	v_lshlrev_b32_e32 v128, 16, v40
	v_and_b32_e32 v130, 0xffff0000, v40
	v_lshlrev_b32_e32 v131, 16, v41
	v_and_b32_e32 v140, 0xffff0000, v41
	v_lshlrev_b32_e32 v141, 16, v42
	v_and_b32_e32 v142, 0xffff0000, v42
	v_lshlrev_b32_e32 v143, 16, v43
	v_and_b32_e32 v144, 0xffff0000, v43
	v_fmac_f32_e32 v138, v129, v128
	v_fmac_f32_e32 v139, v129, v130
	v_fmac_f32_e32 v132, v129, v131
	v_fmac_f32_e32 v133, v129, v140
	v_fmac_f32_e32 v134, v129, v141
	v_fmac_f32_e32 v135, v129, v142
	v_fmac_f32_e32 v136, v129, v143
	v_fmac_f32_e32 v137, v129, v144
	ds_read2_b32 v[128:129], v155 offset0:96 offset1:112
	v_lshlrev_b32_e32 v130, 16, v48
	v_and_b32_e32 v131, 0xffff0000, v48
	v_lshlrev_b32_e32 v140, 16, v49
	v_and_b32_e32 v141, 0xffff0000, v49
	v_lshlrev_b32_e32 v142, 16, v50
	v_and_b32_e32 v143, 0xffff0000, v50
	v_lshlrev_b32_e32 v144, 16, v51
	v_and_b32_e32 v145, 0xffff0000, v51
	s_waitcnt lgkmcnt(0)
	v_fmac_f32_e32 v138, v128, v130
	v_fmac_f32_e32 v139, v128, v131
	v_fmac_f32_e32 v132, v128, v140
	v_fmac_f32_e32 v133, v128, v141
	v_fmac_f32_e32 v134, v128, v142
	v_fmac_f32_e32 v135, v128, v143
	v_fmac_f32_e32 v136, v128, v144
	v_fmac_f32_e32 v137, v128, v145
	v_lshlrev_b32_e32 v128, 16, v56
	v_and_b32_e32 v130, 0xffff0000, v56
	v_lshlrev_b32_e32 v131, 16, v57
	v_and_b32_e32 v140, 0xffff0000, v57
	v_lshlrev_b32_e32 v141, 16, v58
	v_and_b32_e32 v142, 0xffff0000, v58
	v_lshlrev_b32_e32 v143, 16, v59
	v_and_b32_e32 v144, 0xffff0000, v59
	v_fmac_f32_e32 v138, v129, v128
	v_fmac_f32_e32 v139, v129, v130
	v_fmac_f32_e32 v132, v129, v131
	v_fmac_f32_e32 v133, v129, v140
	v_fmac_f32_e32 v134, v129, v141
	v_fmac_f32_e32 v135, v129, v142
	v_fmac_f32_e32 v136, v129, v143
	v_fmac_f32_e32 v137, v129, v144
	ds_read2_b32 v[128:129], v155 offset0:128 offset1:144
	v_lshlrev_b32_e32 v130, 16, v64
	v_and_b32_e32 v131, 0xffff0000, v64
	v_lshlrev_b32_e32 v140, 16, v65
	v_and_b32_e32 v141, 0xffff0000, v65
	v_lshlrev_b32_e32 v142, 16, v66
	v_and_b32_e32 v143, 0xffff0000, v66
	v_lshlrev_b32_e32 v144, 16, v67
	v_and_b32_e32 v145, 0xffff0000, v67
	s_waitcnt lgkmcnt(0)
	v_fmac_f32_e32 v138, v128, v130
	v_fmac_f32_e32 v139, v128, v131
	v_fmac_f32_e32 v132, v128, v140
	v_fmac_f32_e32 v133, v128, v141
	v_fmac_f32_e32 v134, v128, v142
	v_fmac_f32_e32 v135, v128, v143
	v_fmac_f32_e32 v136, v128, v144
	v_fmac_f32_e32 v137, v128, v145
	v_lshlrev_b32_e32 v128, 16, v72
	v_and_b32_e32 v130, 0xffff0000, v72
	v_lshlrev_b32_e32 v131, 16, v73
	v_and_b32_e32 v140, 0xffff0000, v73
	v_lshlrev_b32_e32 v141, 16, v74
	v_and_b32_e32 v142, 0xffff0000, v74
	v_lshlrev_b32_e32 v143, 16, v75
	v_and_b32_e32 v144, 0xffff0000, v75
	v_fmac_f32_e32 v138, v129, v128
	v_fmac_f32_e32 v139, v129, v130
	v_fmac_f32_e32 v132, v129, v131
	v_fmac_f32_e32 v133, v129, v140
	v_fmac_f32_e32 v134, v129, v141
	v_fmac_f32_e32 v135, v129, v142
	v_fmac_f32_e32 v136, v129, v143
	v_fmac_f32_e32 v137, v129, v144
	ds_read2_b32 v[128:129], v155 offset0:160 offset1:176
	v_lshlrev_b32_e32 v130, 16, v80
	v_and_b32_e32 v131, 0xffff0000, v80
	v_lshlrev_b32_e32 v140, 16, v81
	v_and_b32_e32 v141, 0xffff0000, v81
	v_lshlrev_b32_e32 v142, 16, v82
	v_and_b32_e32 v143, 0xffff0000, v82
	v_lshlrev_b32_e32 v144, 16, v83
	v_and_b32_e32 v145, 0xffff0000, v83
	s_waitcnt lgkmcnt(0)
	v_fmac_f32_e32 v138, v128, v130
	v_fmac_f32_e32 v139, v128, v131
	v_fmac_f32_e32 v132, v128, v140
	v_fmac_f32_e32 v133, v128, v141
	v_fmac_f32_e32 v134, v128, v142
	v_fmac_f32_e32 v135, v128, v143
	v_fmac_f32_e32 v136, v128, v144
	v_fmac_f32_e32 v137, v128, v145
	v_lshlrev_b32_e32 v128, 16, v88
	v_and_b32_e32 v130, 0xffff0000, v88
	v_lshlrev_b32_e32 v131, 16, v89
	v_and_b32_e32 v140, 0xffff0000, v89
	v_lshlrev_b32_e32 v141, 16, v90
	v_and_b32_e32 v142, 0xffff0000, v90
	v_lshlrev_b32_e32 v143, 16, v91
	v_and_b32_e32 v144, 0xffff0000, v91
	v_fmac_f32_e32 v138, v129, v128
	v_fmac_f32_e32 v139, v129, v130
	v_fmac_f32_e32 v132, v129, v131
	v_fmac_f32_e32 v133, v129, v140
	v_fmac_f32_e32 v134, v129, v141
	v_fmac_f32_e32 v135, v129, v142
	v_fmac_f32_e32 v136, v129, v143
	v_fmac_f32_e32 v137, v129, v144
	ds_read2_b32 v[128:129], v155 offset0:192 offset1:208
	v_lshlrev_b32_e32 v130, 16, v96
	v_and_b32_e32 v131, 0xffff0000, v96
	v_lshlrev_b32_e32 v140, 16, v97
	v_and_b32_e32 v141, 0xffff0000, v97
	v_lshlrev_b32_e32 v142, 16, v98
	v_and_b32_e32 v143, 0xffff0000, v98
	v_lshlrev_b32_e32 v144, 16, v99
	v_and_b32_e32 v145, 0xffff0000, v99
	s_waitcnt lgkmcnt(0)
; __device__ __forceinline__ void dsa_tile(const Params& p, unsigned char* smem, int tile) {
;     ...
;         u32x4 chi[2], clo[2];
; #pragma unroll
;         for (int ks = 0; ks < 2; ++ks) {
;             float c[8];
; #pragma unroll
;             for (int e = 0; e < 8; ++e) c[e] = 0.f;
; #pragma unroll
;             for (int h = 0; h < 16; ++h) { const float wh = wl[h * 16 + fr]; float f[8]; unpack8(yf[h][ks], f);
; #pragma unroll
;                 for (int e = 0; e < 8; ++e) c[e] += wh * f[e]; }
;             chi[ks] = pack8(c);
;             float fh[8]; unpack8(chi[ks], fh);
; #pragma unroll
;             for (int e = 0; e < 8; ++e) c[e] -= fh[e];
;             clo[ks] = pack8(c);
;         }
;         float wv[16];
; #pragma unroll
;         for (int h = 0; h < 16; ++h) wv[h] = wl[h * 16 + fr];
	v_fmac_f32_e32 v138, v128, v130
	v_fmac_f32_e32 v139, v128, v131
	v_fmac_f32_e32 v132, v128, v140
	v_fmac_f32_e32 v133, v128, v141
	v_fmac_f32_e32 v134, v128, v142
	v_fmac_f32_e32 v135, v128, v143
	v_fmac_f32_e32 v136, v128, v144
	v_fmac_f32_e32 v137, v128, v145
	v_lshlrev_b32_e32 v128, 16, v104
	v_and_b32_e32 v130, 0xffff0000, v104
	v_lshlrev_b32_e32 v131, 16, v105
	v_and_b32_e32 v140, 0xffff0000, v105
	v_lshlrev_b32_e32 v141, 16, v106
	v_and_b32_e32 v142, 0xffff0000, v106
	v_lshlrev_b32_e32 v143, 16, v107
	v_and_b32_e32 v144, 0xffff0000, v107
	v_fmac_f32_e32 v138, v129, v128
	v_fmac_f32_e32 v139, v129, v130
	v_fmac_f32_e32 v132, v129, v131
	v_fmac_f32_e32 v133, v129, v140
	v_fmac_f32_e32 v134, v129, v141
	v_fmac_f32_e32 v135, v129, v142
	v_fmac_f32_e32 v136, v129, v143
	v_fmac_f32_e32 v137, v129, v144
	ds_read2_b32 v[128:129], v155 offset0:224 offset1:240
	v_lshlrev_b32_e32 v130, 16, v112
	v_and_b32_e32 v131, 0xffff0000, v112
	v_lshlrev_b32_e32 v140, 16, v113
	v_and_b32_e32 v141, 0xffff0000, v113
	v_lshlrev_b32_e32 v142, 16, v114
	v_and_b32_e32 v143, 0xffff0000, v114
	v_lshlrev_b32_e32 v144, 16, v115
	v_and_b32_e32 v145, 0xffff0000, v115
	s_waitcnt lgkmcnt(0)
	v_fmac_f32_e32 v138, v128, v130
	v_fmac_f32_e32 v139, v128, v131
	v_fmac_f32_e32 v132, v128, v140
	v_fmac_f32_e32 v133, v128, v141
	v_fmac_f32_e32 v134, v128, v142
	v_fmac_f32_e32 v135, v128, v143
	v_fmac_f32_e32 v136, v128, v144
	v_fmac_f32_e32 v137, v128, v145
	v_lshlrev_b32_e32 v128, 16, v120
	v_and_b32_e32 v130, 0xffff0000, v120
	v_lshlrev_b32_e32 v131, 16, v121
	v_and_b32_e32 v140, 0xffff0000, v121
	v_lshlrev_b32_e32 v141, 16, v122
	v_and_b32_e32 v142, 0xffff0000, v122
	v_lshlrev_b32_e32 v143, 16, v123
	v_and_b32_e32 v144, 0xffff0000, v123
	v_fmac_f32_e32 v138, v129, v128
	v_fmac_f32_e32 v139, v129, v130
	v_fmac_f32_e32 v132, v129, v131
	v_fmac_f32_e32 v133, v129, v140
	v_fmac_f32_e32 v134, v129, v141
	v_fmac_f32_e32 v135, v129, v142
	v_fmac_f32_e32 v136, v129, v143
	v_fmac_f32_e32 v137, v129, v144
	v_cvt_pk_bf16_f32 v128, v138, v139
	v_cvt_pk_bf16_f32 v129, v132, v133
	v_cvt_pk_bf16_f32 v130, v134, v135
	v_cvt_pk_bf16_f32 v131, v136, v137
	v_and_b32_e32 v148, 0xffff0000, v13
	v_and_b32_e32 v143, 0xffff0000, v129
	v_lshlrev_b32_e32 v144, 16, v130
	v_and_b32_e32 v145, 0xffff0000, v130
	v_lshlrev_b32_e32 v146, 16, v131
	v_and_b32_e32 v147, 0xffff0000, v131
	v_lshlrev_b32_e32 v140, 16, v128
	v_and_b32_e32 v141, 0xffff0000, v128
	v_lshlrev_b32_e32 v142, 16, v129
	v_sub_f32_e32 v133, v133, v143
	v_sub_f32_e32 v134, v134, v144
	v_sub_f32_e32 v135, v135, v145
	v_sub_f32_e32 v136, v136, v146
	v_sub_f32_e32 v137, v137, v147
	v_sub_f32_e32 v138, v138, v140
	v_sub_f32_e32 v139, v139, v141
	v_sub_f32_e32 v140, v132, v142
	v_cvt_pk_bf16_f32 v132, v138, v139
	v_cvt_pk_bf16_f32 v133, v140, v133
	v_cvt_pk_bf16_f32 v134, v134, v135
	v_cvt_pk_bf16_f32 v135, v136, v137
	ds_read2_b32 v[136:137], v155 offset1:16
	v_lshlrev_b32_e32 v138, 16, v4
	v_and_b32_e32 v139, 0xffff0000, v4
	v_lshlrev_b32_e32 v140, 16, v5
	v_and_b32_e32 v141, 0xffff0000, v5
	v_lshlrev_b32_e32 v142, 16, v6
	v_and_b32_e32 v143, 0xffff0000, v6
	v_lshlrev_b32_e32 v144, 16, v7
	v_and_b32_e32 v145, 0xffff0000, v7
	s_waitcnt lgkmcnt(0)
	v_fma_f32 v146, v136, v138, 0
	v_fma_f32 v147, v136, v139, 0
	v_fma_f32 v140, v136, v140, 0
	v_fma_f32 v141, v136, v141, 0
	v_fma_f32 v142, v136, v142, 0
	v_fma_f32 v143, v136, v143, 0
	v_fma_f32 v144, v136, v144, 0
	v_fma_f32 v145, v136, v145, 0
	v_lshlrev_b32_e32 v136, 16, v12
	v_and_b32_e32 v138, 0xffff0000, v12
	v_lshlrev_b32_e32 v139, 16, v13
	v_lshlrev_b32_e32 v149, 16, v14
	v_and_b32_e32 v150, 0xffff0000, v14
	v_lshlrev_b32_e32 v151, 16, v15
	v_and_b32_e32 v156, 0xffff0000, v15
	v_fmac_f32_e32 v146, v137, v136
	v_fmac_f32_e32 v147, v137, v138
	v_fmac_f32_e32 v140, v137, v139
	v_fmac_f32_e32 v141, v137, v148
	v_fmac_f32_e32 v142, v137, v149
	v_fmac_f32_e32 v143, v137, v150
	v_fmac_f32_e32 v144, v137, v151
	v_fmac_f32_e32 v145, v137, v156
	ds_read2_b32 v[136:137], v155 offset0:32 offset1:48
	v_lshlrev_b32_e32 v138, 16, v20
	v_and_b32_e32 v139, 0xffff0000, v20
	v_lshlrev_b32_e32 v148, 16, v21
	v_and_b32_e32 v149, 0xffff0000, v21
	v_lshlrev_b32_e32 v150, 16, v22
	v_and_b32_e32 v151, 0xffff0000, v22
	v_lshlrev_b32_e32 v156, 16, v23
	v_and_b32_e32 v157, 0xffff0000, v23
	s_waitcnt lgkmcnt(0)
	v_fmac_f32_e32 v146, v136, v138
	v_fmac_f32_e32 v147, v136, v139
	v_fmac_f32_e32 v140, v136, v148
	v_fmac_f32_e32 v141, v136, v149
	v_fmac_f32_e32 v142, v136, v150
	v_fmac_f32_e32 v143, v136, v151
	v_fmac_f32_e32 v144, v136, v156
	v_fmac_f32_e32 v145, v136, v157
	v_lshlrev_b32_e32 v136, 16, v28
	v_and_b32_e32 v138, 0xffff0000, v28
	v_lshlrev_b32_e32 v139, 16, v29
	v_and_b32_e32 v148, 0xffff0000, v29
	v_lshlrev_b32_e32 v149, 16, v30
	v_and_b32_e32 v150, 0xffff0000, v30
	v_lshlrev_b32_e32 v151, 16, v31
	v_and_b32_e32 v156, 0xffff0000, v31
	v_fmac_f32_e32 v146, v137, v136
	v_fmac_f32_e32 v147, v137, v138
	v_fmac_f32_e32 v140, v137, v139
	v_fmac_f32_e32 v141, v137, v148
	v_fmac_f32_e32 v142, v137, v149
	v_fmac_f32_e32 v143, v137, v150
	v_fmac_f32_e32 v144, v137, v151
	v_fmac_f32_e32 v145, v137, v156
	ds_read2_b32 v[136:137], v155 offset0:64 offset1:80
	v_lshlrev_b32_e32 v138, 16, v36
	v_and_b32_e32 v139, 0xffff0000, v36
	v_lshlrev_b32_e32 v148, 16, v37
	v_and_b32_e32 v149, 0xffff0000, v37
	v_lshlrev_b32_e32 v150, 16, v38
	v_and_b32_e32 v151, 0xffff0000, v38
	v_lshlrev_b32_e32 v156, 16, v39
	v_and_b32_e32 v157, 0xffff0000, v39
	s_waitcnt lgkmcnt(0)
; __device__ __forceinline__ void dsa_tile(const Params& p, unsigned char* smem, int tile) {
;     ...
;             for (int h = 0; h < 16; ++h) { const float wh = wl[h * 16 + fr]; float f[8]; unpack8(yf[h][ks], f);
; #pragma unroll
;                 for (int e = 0; e < 8; ++e) c[e] += wh * f[e]; }
	v_fmac_f32_e32 v146, v136, v138
	v_fmac_f32_e32 v147, v136, v139
	v_fmac_f32_e32 v140, v136, v148
	v_fmac_f32_e32 v141, v136, v149
	v_fmac_f32_e32 v142, v136, v150
	v_fmac_f32_e32 v143, v136, v151
	v_fmac_f32_e32 v144, v136, v156
	v_fmac_f32_e32 v145, v136, v157
	v_lshlrev_b32_e32 v136, 16, v44
	v_and_b32_e32 v138, 0xffff0000, v44
	v_lshlrev_b32_e32 v139, 16, v45
	v_and_b32_e32 v148, 0xffff0000, v45
	v_lshlrev_b32_e32 v149, 16, v46
	v_and_b32_e32 v150, 0xffff0000, v46
	v_lshlrev_b32_e32 v151, 16, v47
	v_and_b32_e32 v156, 0xffff0000, v47
	v_fmac_f32_e32 v146, v137, v136
	v_fmac_f32_e32 v147, v137, v138
	v_fmac_f32_e32 v140, v137, v139
	v_fmac_f32_e32 v141, v137, v148
	v_fmac_f32_e32 v142, v137, v149
	v_fmac_f32_e32 v143, v137, v150
	v_fmac_f32_e32 v144, v137, v151
	v_fmac_f32_e32 v145, v137, v156
	ds_read2_b32 v[136:137], v155 offset0:96 offset1:112
	v_lshlrev_b32_e32 v138, 16, v52
	v_and_b32_e32 v139, 0xffff0000, v52
	v_lshlrev_b32_e32 v148, 16, v53
	v_and_b32_e32 v149, 0xffff0000, v53
	v_lshlrev_b32_e32 v150, 16, v54
	v_and_b32_e32 v151, 0xffff0000, v54
	v_lshlrev_b32_e32 v156, 16, v55
	v_and_b32_e32 v157, 0xffff0000, v55
	s_waitcnt lgkmcnt(0)
	v_fmac_f32_e32 v146, v136, v138
	v_fmac_f32_e32 v147, v136, v139
	v_fmac_f32_e32 v140, v136, v148
	v_fmac_f32_e32 v141, v136, v149
	v_fmac_f32_e32 v142, v136, v150
	v_fmac_f32_e32 v143, v136, v151
	v_fmac_f32_e32 v144, v136, v156
	v_fmac_f32_e32 v145, v136, v157
	v_lshlrev_b32_e32 v136, 16, v60
	v_and_b32_e32 v138, 0xffff0000, v60
	v_lshlrev_b32_e32 v139, 16, v61
	v_and_b32_e32 v148, 0xffff0000, v61
	v_lshlrev_b32_e32 v149, 16, v62
	v_and_b32_e32 v150, 0xffff0000, v62
	v_lshlrev_b32_e32 v151, 16, v63
	v_and_b32_e32 v156, 0xffff0000, v63
	v_fmac_f32_e32 v146, v137, v136
	v_fmac_f32_e32 v147, v137, v138
	v_fmac_f32_e32 v140, v137, v139
	v_fmac_f32_e32 v141, v137, v148
	v_fmac_f32_e32 v142, v137, v149
	v_fmac_f32_e32 v143, v137, v150
	v_fmac_f32_e32 v144, v137, v151
	v_fmac_f32_e32 v145, v137, v156
	ds_read2_b32 v[136:137], v155 offset0:128 offset1:144
	v_lshlrev_b32_e32 v138, 16, v68
	v_and_b32_e32 v139, 0xffff0000, v68
	v_lshlrev_b32_e32 v148, 16, v69
	v_and_b32_e32 v149, 0xffff0000, v69
	v_lshlrev_b32_e32 v150, 16, v70
	v_and_b32_e32 v151, 0xffff0000, v70
	v_lshlrev_b32_e32 v156, 16, v71
	v_and_b32_e32 v157, 0xffff0000, v71
	s_waitcnt lgkmcnt(0)
	v_fmac_f32_e32 v146, v136, v138
	v_fmac_f32_e32 v147, v136, v139
	v_fmac_f32_e32 v140, v136, v148
	v_fmac_f32_e32 v141, v136, v149
	v_fmac_f32_e32 v142, v136, v150
	v_fmac_f32_e32 v143, v136, v151
	v_fmac_f32_e32 v144, v136, v156
	v_fmac_f32_e32 v145, v136, v157
	v_lshlrev_b32_e32 v136, 16, v76
	v_and_b32_e32 v138, 0xffff0000, v76
	v_lshlrev_b32_e32 v139, 16, v77
	v_and_b32_e32 v148, 0xffff0000, v77
	v_lshlrev_b32_e32 v149, 16, v78
	v_and_b32_e32 v150, 0xffff0000, v78
	v_lshlrev_b32_e32 v151, 16, v79
	v_and_b32_e32 v156, 0xffff0000, v79
	v_fmac_f32_e32 v146, v137, v136
	v_fmac_f32_e32 v147, v137, v138
	v_fmac_f32_e32 v140, v137, v139
	v_fmac_f32_e32 v141, v137, v148
	v_fmac_f32_e32 v142, v137, v149
	v_fmac_f32_e32 v143, v137, v150
	v_fmac_f32_e32 v144, v137, v151
	v_fmac_f32_e32 v145, v137, v156
	ds_read2_b32 v[136:137], v155 offset0:160 offset1:176
	v_lshlrev_b32_e32 v138, 16, v84
	v_and_b32_e32 v139, 0xffff0000, v84
	v_lshlrev_b32_e32 v148, 16, v85
	v_and_b32_e32 v149, 0xffff0000, v85
	v_lshlrev_b32_e32 v150, 16, v86
	v_and_b32_e32 v151, 0xffff0000, v86
	v_lshlrev_b32_e32 v156, 16, v87
	v_and_b32_e32 v157, 0xffff0000, v87
	s_waitcnt lgkmcnt(0)
	v_fmac_f32_e32 v146, v136, v138
	v_fmac_f32_e32 v147, v136, v139
	v_fmac_f32_e32 v140, v136, v148
	v_fmac_f32_e32 v141, v136, v149
	v_fmac_f32_e32 v142, v136, v150
	v_fmac_f32_e32 v143, v136, v151
	v_fmac_f32_e32 v144, v136, v156
	v_fmac_f32_e32 v145, v136, v157
	v_lshlrev_b32_e32 v136, 16, v92
	v_and_b32_e32 v138, 0xffff0000, v92
	v_lshlrev_b32_e32 v139, 16, v93
	v_and_b32_e32 v148, 0xffff0000, v93
	v_lshlrev_b32_e32 v149, 16, v94
	v_and_b32_e32 v150, 0xffff0000, v94
	v_lshlrev_b32_e32 v151, 16, v95
	v_and_b32_e32 v156, 0xffff0000, v95
	v_fmac_f32_e32 v146, v137, v136
	v_fmac_f32_e32 v147, v137, v138
	v_fmac_f32_e32 v140, v137, v139
	v_fmac_f32_e32 v141, v137, v148
	v_fmac_f32_e32 v142, v137, v149
	v_fmac_f32_e32 v143, v137, v150
	v_fmac_f32_e32 v144, v137, v151
	v_fmac_f32_e32 v145, v137, v156
	ds_read2_b32 v[136:137], v155 offset0:192 offset1:208
	v_lshlrev_b32_e32 v138, 16, v100
	v_and_b32_e32 v139, 0xffff0000, v100
	v_lshlrev_b32_e32 v148, 16, v101
	v_and_b32_e32 v149, 0xffff0000, v101
	v_lshlrev_b32_e32 v150, 16, v102
	v_and_b32_e32 v151, 0xffff0000, v102
	v_lshlrev_b32_e32 v156, 16, v103
	v_and_b32_e32 v157, 0xffff0000, v103
	s_waitcnt lgkmcnt(0)
	v_fmac_f32_e32 v146, v136, v138
	v_fmac_f32_e32 v147, v136, v139
	v_fmac_f32_e32 v140, v136, v148
	v_fmac_f32_e32 v141, v136, v149
	v_fmac_f32_e32 v142, v136, v150
	v_fmac_f32_e32 v143, v136, v151
	v_fmac_f32_e32 v144, v136, v156
	v_fmac_f32_e32 v145, v136, v157
	v_lshlrev_b32_e32 v136, 16, v108
	v_and_b32_e32 v138, 0xffff0000, v108
	v_lshlrev_b32_e32 v139, 16, v109
	v_and_b32_e32 v148, 0xffff0000, v109
	v_lshlrev_b32_e32 v149, 16, v110
	v_and_b32_e32 v150, 0xffff0000, v110
	v_lshlrev_b32_e32 v151, 16, v111
	v_and_b32_e32 v156, 0xffff0000, v111
	v_fmac_f32_e32 v146, v137, v136
	v_fmac_f32_e32 v147, v137, v138
	v_fmac_f32_e32 v140, v137, v139
	v_fmac_f32_e32 v141, v137, v148
	v_fmac_f32_e32 v142, v137, v149
	v_fmac_f32_e32 v143, v137, v150
	v_fmac_f32_e32 v144, v137, v151
	v_fmac_f32_e32 v145, v137, v156
	ds_read2_b32 v[136:137], v155 offset0:224 offset1:240
	v_lshlrev_b32_e32 v138, 16, v116
	v_and_b32_e32 v139, 0xffff0000, v116
	v_lshlrev_b32_e32 v148, 16, v117
	v_and_b32_e32 v149, 0xffff0000, v117
	v_lshlrev_b32_e32 v150, 16, v118
	v_and_b32_e32 v151, 0xffff0000, v118
	v_lshlrev_b32_e32 v156, 16, v119
	v_and_b32_e32 v157, 0xffff0000, v119
	s_waitcnt lgkmcnt(0)
; __device__ __forceinline__ void dsa_tile(const Params& p, unsigned char* smem, int tile) {
;     ...
;             chi[ks] = pack8(c);
;             float fh[8]; unpack8(chi[ks], fh);
; #pragma unroll
;             for (int e = 0; e < 8; ++e) c[e] -= fh[e];
;             clo[ks] = pack8(c);
;         }
;         float wv[16];
; #pragma unroll
;         for (int h = 0; h < 16; ++h) wv[h] = wl[h * 16 + fr];
;         const int nkb = qt + 1;
;         const bf16_t* kbase = (const bf16_t*)(p.ws + WS_IKC) + (size_t)b * SEQ * 64 + lane * 8;
;         int kb = wid;
;         u32x4 x0 = {0u, 0u, 0u, 0u}, x1 = x0;
;         if (kb < nkb) { const bf16_t* kr = kbase + (size_t)kb * 16 * 64; x0 = *(const u32x4*)kr; x1 = *(const u32x4*)(kr + 512); }
	v_fmac_f32_e32 v146, v136, v138
	v_fmac_f32_e32 v147, v136, v139
	v_fmac_f32_e32 v140, v136, v148
	v_fmac_f32_e32 v141, v136, v149
	v_fmac_f32_e32 v142, v136, v150
	v_fmac_f32_e32 v143, v136, v151
	v_fmac_f32_e32 v144, v136, v156
	v_fmac_f32_e32 v145, v136, v157
	v_lshlrev_b32_e32 v136, 16, v124
	v_and_b32_e32 v138, 0xffff0000, v124
	v_lshlrev_b32_e32 v139, 16, v125
	v_and_b32_e32 v148, 0xffff0000, v125
	v_lshlrev_b32_e32 v149, 16, v126
	v_and_b32_e32 v150, 0xffff0000, v126
	v_lshlrev_b32_e32 v151, 16, v127
	v_and_b32_e32 v156, 0xffff0000, v127
	s_ashr_i32 s10, s15, 6
	v_fmac_f32_e32 v146, v137, v136
	v_fmac_f32_e32 v147, v137, v138
	v_fmac_f32_e32 v140, v137, v139
	v_fmac_f32_e32 v141, v137, v148
	v_fmac_f32_e32 v142, v137, v149
	v_fmac_f32_e32 v143, v137, v150
	v_fmac_f32_e32 v144, v137, v151
	v_fmac_f32_e32 v145, v137, v156
	v_cvt_pk_bf16_f32 v136, v146, v147
	v_cvt_pk_bf16_f32 v137, v140, v141
	v_cvt_pk_bf16_f32 v138, v142, v143
	v_cvt_pk_bf16_f32 v139, v144, v145
	s_cmp_gt_i32 s10, s14
	v_and_b32_e32 v151, 0xffff0000, v137
	v_lshlrev_b32_e32 v156, 16, v138
	v_and_b32_e32 v157, 0xffff0000, v138
	v_lshlrev_b32_e32 v148, 16, v136
	v_and_b32_e32 v149, 0xffff0000, v136
	v_lshlrev_b32_e32 v150, 16, v137
	v_lshlrev_b32_e32 v158, 16, v139
	v_and_b32_e32 v159, 0xffff0000, v139
	v_sub_f32_e32 v141, v141, v151
	v_sub_f32_e32 v142, v142, v156
	v_sub_f32_e32 v143, v143, v157
	v_sub_f32_e32 v146, v146, v148
	v_sub_f32_e32 v147, v147, v149
	v_sub_f32_e32 v148, v140, v150
	v_sub_f32_e32 v144, v144, v158
	v_sub_f32_e32 v145, v145, v159
	v_cvt_pk_bf16_f32 v140, v146, v147
	v_cvt_pk_bf16_f32 v141, v148, v141
	v_cvt_pk_bf16_f32 v142, v142, v143
	v_cvt_pk_bf16_f32 v143, v144, v145
	s_cbranch_scc1 .LBB0_290
	s_lshl_b64 s[4:5], s[8:9], 20
	v_and_b32_e32 v144, 63, v152
	s_add_u32 s4, s88, s4
	s_addc_u32 s5, s89, s5
	v_lshlrev_b32_e32 v160, 4, v144
	s_ashr_i32 s11, s10, 31
	v_lshl_add_u64 v[162:163], s[4:5], 0, v[160:161]
	s_lshl_b64 s[4:5], s[10:11], 11
	v_lshl_add_u64 v[144:145], v[162:163], 0, s[4:5]
	global_load_dwordx4 v[148:151], v[144:145], off
	s_nop 0
	global_load_dwordx4 v[144:147], v[144:145], off offset:1024
	v_add_u32_e32 v186, 0xa200, v154
	v_add_u32_e32 v187, 0xa240, v154
	v_add_u32_e32 v188, 0xa280, v154
	v_add_u32_e32 v189, 0xa2c0, v154
	v_add_u32_e32 v190, 0xa300, v154
	v_add_u32_e32 v191, 0xa340, v154
	v_add_u32_e32 v192, 0xa380, v154
	v_add_u32_e32 v156, 0xa040, v154
	v_add_u32_e32 v157, 0xa080, v154
	v_add_u32_e32 v158, 0xa0c0, v154
	v_add_u32_e32 v159, 0xa100, v154
	v_add_u32_e32 v160, 0xa140, v154
	v_add_u32_e32 v164, 0xa180, v154
	v_add_u32_e32 v165, 0xa1c0, v154
	v_add_u32_e32 v154, 0xa3c0, v154
	ds_read_b32 v178, v155
	ds_read_b32 v179, v156
	ds_read_b32 v180, v157
	ds_read_b32 v181, v158
	ds_read_b32 v182, v159
	ds_read_b32 v183, v160
	ds_read_b32 v184, v164
	ds_read_b32 v185, v165
	ds_read_b32 v186, v186
	ds_read_b32 v187, v187
	ds_read_b32 v188, v188
	ds_read_b32 v189, v189
	ds_read_b32 v190, v190
	ds_read_b32 v191, v191
	ds_read_b32 v192, v192
	ds_read_b32 v193, v154
	s_lshl_b32 s4, s10, 4
	s_ashr_i32 s5, s4, 31
	s_lshl_b64 s[4:5], s[4:5], 2
	v_and_b32_e32 v152, 48, v152
	s_add_u32 s4, s92, s4
	v_lshl_or_b32 v160, v153, 15, v152
	s_addc_u32 s5, s93, s5
	v_lshl_add_u64 v[164:165], s[4:5], 0, v[160:161]
	s_mov_b32 s12, s10
	s_waitcnt vmcnt(0) lgkmcnt(0)
; __device__ __forceinline__ void dsa_tile(const Params& p, unsigned char* smem, int tile) {
;     ...
;         for (; kb < nkb; kb += 8) {
;             const int kn = (kb + 8 < nkb) ? kb + 8 : kb;
;             const bf16_t* kr = kbase + (size_t)kn * 16 * 64;
;             const u32x4 nx0 = *(const u32x4*)kr, nx1 = *(const u32x4*)(kr + 512);
;             f32x4 s = {0, 0, 0, 0};
;             s = mfma16(x0, chi[0], s); s = mfma16(x1, chi[1], s); s = mfma16(x0, clo[0], s); s = mfma16(x1, clo[1], s);
; #pragma unroll
;             for (int h = 0; h < 16; ++h) {
;                 if ((h & 7) == 0) __builtin_amdgcn_sched_barrier(0);
;                 const float wh = wv[h];
;                 f32x4 d = {0, 0, 0, 0};
;                 d = mfma16(x0, yf[h][0], d); d = mfma16(x1, yf[h][1], d);
; #pragma unroll
;                 for (int j = 0; j < 4; ++j) { float a = __builtin_fmaf(wh, __builtin_fabsf(d[j]), s[j]); asm("" : "+v"(a)); s[j] = a; }
;             }
;             *(f32x4*)(sc + (size_t)fr * SEQ + kb * 16 + fq * 4) = s;
;             x0 = nx0; x1 = nx1;
;         }
.LBB0_289:
	s_add_i32 s11, s12, 8
	s_cmp_gt_i32 s11, s14
	s_cselect_b32 s4, s12, s11
	s_ashr_i32 s5, s4, 31
	s_lshl_b64 s[4:5], s[4:5], 11
	v_lshl_add_u64 v[228:229], v[162:163], 0, s[4:5]
	v_mfma_f32_16x16x32_bf16 v[230:233], v[148:151], v[128:131], 0
	global_load_dwordx4 v[156:159], v[228:229], off
	v_mfma_f32_16x16x32_bf16 v[230:233], v[144:147], v[136:139], v[230:233]
	global_load_dwordx4 v[152:155], v[228:229], off offset:1024
	v_mfma_f32_16x16x32_bf16 v[230:233], v[148:151], v[132:135], v[230:233]
	v_mfma_f32_16x16x32_bf16 v[230:233], v[144:147], v[140:143], v[230:233]
	v_mfma_f32_16x16x32_bf16 v[194:197], v[148:151], v[0:3], 0
	v_mfma_f32_16x16x32_bf16 v[198:201], v[148:151], v[8:11], 0
	v_mfma_f32_16x16x32_bf16 v[202:205], v[148:151], v[16:19], 0
	v_mfma_f32_16x16x32_bf16 v[206:209], v[148:151], v[24:27], 0
	v_mfma_f32_16x16x32_bf16 v[194:197], v[144:147], v[4:7], v[194:197]
	v_mfma_f32_16x16x32_bf16 v[198:201], v[144:147], v[12:15], v[198:201]
	v_mfma_f32_16x16x32_bf16 v[202:205], v[144:147], v[20:23], v[202:205]
	v_mfma_f32_16x16x32_bf16 v[206:209], v[144:147], v[28:31], v[206:209]
	v_mfma_f32_16x16x32_bf16 v[210:213], v[148:151], v[32:35], 0
	s_nop 3
	v_fma_f32 v230, v178, |v194|, v230
	v_fma_f32 v231, v178, |v195|, v231
	v_mfma_f32_16x16x32_bf16 v[214:217], v[148:151], v[40:43], 0
	v_fma_f32 v232, v178, |v196|, v232
	v_fma_f32 v233, v178, |v197|, v233
	v_mfma_f32_16x16x32_bf16 v[218:221], v[148:151], v[48:51], 0
	v_fma_f32 v230, v179, |v198|, v230
	v_fma_f32 v231, v179, |v199|, v231
	v_mfma_f32_16x16x32_bf16 v[222:225], v[148:151], v[56:59], 0
	v_fma_f32 v232, v179, |v200|, v232
	v_fma_f32 v233, v179, |v201|, v233
	v_mfma_f32_16x16x32_bf16 v[210:213], v[144:147], v[36:39], v[210:213]
	v_fma_f32 v230, v180, |v202|, v230
	v_fma_f32 v231, v180, |v203|, v231
	v_mfma_f32_16x16x32_bf16 v[214:217], v[144:147], v[44:47], v[214:217]
	v_fma_f32 v232, v180, |v204|, v232
	v_fma_f32 v233, v180, |v205|, v233
	v_mfma_f32_16x16x32_bf16 v[218:221], v[144:147], v[52:55], v[218:221]
	v_fma_f32 v230, v181, |v206|, v230
	v_fma_f32 v231, v181, |v207|, v231
	v_mfma_f32_16x16x32_bf16 v[222:225], v[144:147], v[60:63], v[222:225]
	v_fma_f32 v232, v181, |v208|, v232
	v_fma_f32 v233, v181, |v209|, v233
	v_mfma_f32_16x16x32_bf16 v[194:197], v[148:151], v[64:67], 0
	v_fma_f32 v230, v182, |v210|, v230
	v_fma_f32 v231, v182, |v211|, v231
	v_mfma_f32_16x16x32_bf16 v[198:201], v[148:151], v[72:75], 0
	v_fma_f32 v232, v182, |v212|, v232
	v_fma_f32 v233, v182, |v213|, v233
	v_mfma_f32_16x16x32_bf16 v[202:205], v[148:151], v[80:83], 0
	v_fma_f32 v230, v183, |v214|, v230
	v_fma_f32 v231, v183, |v215|, v231
	v_mfma_f32_16x16x32_bf16 v[206:209], v[148:151], v[88:91], 0
	v_fma_f32 v232, v183, |v216|, v232
	v_fma_f32 v233, v183, |v217|, v233
	v_mfma_f32_16x16x32_bf16 v[194:197], v[144:147], v[68:71], v[194:197]
	v_fma_f32 v230, v184, |v218|, v230
	v_fma_f32 v231, v184, |v219|, v231
	v_mfma_f32_16x16x32_bf16 v[198:201], v[144:147], v[76:79], v[198:201]
	v_fma_f32 v232, v184, |v220|, v232
	v_fma_f32 v233, v184, |v221|, v233
	v_mfma_f32_16x16x32_bf16 v[202:205], v[144:147], v[84:87], v[202:205]
	v_fma_f32 v230, v185, |v222|, v230
	v_fma_f32 v231, v185, |v223|, v231
	v_mfma_f32_16x16x32_bf16 v[206:209], v[144:147], v[92:95], v[206:209]
	v_fma_f32 v232, v185, |v224|, v232
	v_fma_f32 v233, v185, |v225|, v233
	v_mfma_f32_16x16x32_bf16 v[210:213], v[148:151], v[96:99], 0
	v_fma_f32 v230, v186, |v194|, v230
	v_fma_f32 v231, v186, |v195|, v231
	v_mfma_f32_16x16x32_bf16 v[214:217], v[148:151], v[104:107], 0
	v_fma_f32 v232, v186, |v196|, v232
	v_fma_f32 v233, v186, |v197|, v233
	v_mfma_f32_16x16x32_bf16 v[218:221], v[148:151], v[112:115], 0
	v_fma_f32 v230, v187, |v198|, v230
	v_fma_f32 v231, v187, |v199|, v231
	v_mfma_f32_16x16x32_bf16 v[222:225], v[148:151], v[120:123], 0
	v_fma_f32 v232, v187, |v200|, v232
	v_fma_f32 v233, v187, |v201|, v233
	v_mfma_f32_16x16x32_bf16 v[210:213], v[144:147], v[100:103], v[210:213]
	v_fma_f32 v230, v188, |v202|, v230
	v_fma_f32 v231, v188, |v203|, v231
	v_mfma_f32_16x16x32_bf16 v[214:217], v[144:147], v[108:111], v[214:217]
	v_fma_f32 v232, v188, |v204|, v232
	v_fma_f32 v233, v188, |v205|, v233
	v_mfma_f32_16x16x32_bf16 v[218:221], v[144:147], v[116:119], v[218:221]
	v_fma_f32 v230, v189, |v206|, v230
	v_fma_f32 v231, v189, |v207|, v231
	v_mfma_f32_16x16x32_bf16 v[222:225], v[144:147], v[124:127], v[222:225]
	v_fma_f32 v232, v189, |v208|, v232
	v_fma_f32 v233, v189, |v209|, v233
	v_fma_f32 v230, v190, |v210|, v230
	v_fma_f32 v231, v190, |v211|, v231
	v_fma_f32 v232, v190, |v212|, v232
	v_fma_f32 v233, v190, |v213|, v233
	v_fma_f32 v230, v191, |v214|, v230
	v_fma_f32 v231, v191, |v215|, v231
	v_fma_f32 v232, v191, |v216|, v232
	v_fma_f32 v233, v191, |v217|, v233
	v_fma_f32 v230, v192, |v218|, v230
	v_fma_f32 v231, v192, |v219|, v231
	v_fma_f32 v232, v192, |v220|, v232
	v_fma_f32 v233, v192, |v221|, v233
	v_fma_f32 v230, v193, |v222|, v230
	v_fma_f32 v231, v193, |v223|, v231
	v_fma_f32 v232, v193, |v224|, v232
	v_fma_f32 v233, v193, |v225|, v233
	s_waitcnt vmcnt(0)
	v_mov_b64_e32 v[148:149], v[156:157]
	v_mov_b64_e32 v[150:151], v[158:159]
	v_mov_b64_e32 v[144:145], v[152:153]
	v_mov_b64_e32 v[146:147], v[154:155]
	s_mov_b64 s[4:5], 0x200
	global_store_dwordx4 v[164:165], v[230:233], off
	v_lshl_add_u64 v[164:165], v[164:165], 0, s[4:5]
	s_mov_b32 s12, s11
	s_cmp_le_i32 s11, s14
	s_cbranch_scc1 .LBB0_289
